# SEAM1 XCC-local in placement-verified mode: rope tables moved to d_out+16MiB (no LSE write-after-read hazard), verdict computed during SEAM0 when the id table is complete, SEAM3 cross-XCC generation a
# speedup vs baseline: 1.0092x; 1.0092x over previous
; __device__ __forceinline__ void p0_prologue(const Ptrs& P, LAS unsigned char* lds, int vcu, int G) {
;     ...
;     float* cosT = (float*)(P.ws + WS_COS); float* sinT = (float*)(P.ws + WS_SIN);
;     for (int e = (vcu * 512 + tid); e < TT * 32; e += G * 512) {
;         const int row = e >> 5, j = e & 31;
;         const float inv = exp2f(-(float)j * (13.287712379549449f / 32.0f));
;         const float ang = (float)P.pos[row] * inv;
;         const double rev = (double)ang * 0.15915494309189535; const float fr = (float)(rev - __builtin_rint(rev));
.LBB0_58:
	v_lshl_add_u32 v0, s16, 9, v188
	s_mov_b32 s0, 0x80000
	v_cmp_gt_i32_e32 vcc, s0, v0
	s_and_saveexec_b64 s[0:1], vcc
	s_cbranch_execz .LBB0_61
	v_cvt_f32_ubyte0_e32 v1, v24
	v_mul_f32_e32 v2, 0xbed49a78, v1
	s_mov_b32 s6, 0xc2fc0000
	v_not_b32_e32 v3, 63
	v_cmp_gt_f32_e32 vcc, s6, v2
	s_lshl_b32 s6, s80, 9
	s_mov_b64 s[8:9], 0x1000000
	v_cndmask_b32_e32 v2, 0, v3, vcc
	v_mov_b32_e32 v3, 0x42800000
	v_cndmask_b32_e32 v3, 0, v3, vcc
	v_fmac_f32_e32 v3, 0xbed49a78, v1
	v_exp_f32_e32 v1, v3
	s_ashr_i32 s7, s6, 31
	s_mov_b32 s12, 0x6dc9c883
	s_mov_b64 s[10:11], 0
	v_ldexp_f32 v4, v1, v2
	v_ashrrev_i32_e32 v1, 31, v0
	v_lshl_add_u64 v[2:3], v[0:1], 2, s[76:77]
	v_lshl_add_u64 v[2:3], v[2:3], 0, s[8:9]
	s_lshl_b64 s[8:9], s[6:7], 2
	s_mov_b32 s13, 0x3fc45f30
	s_mov_b32 s7, 0x7ffff

; __device__ __forceinline__ void xcd_barrier(const XcdBarrier& b) {
;     asm volatile("s_waitcnt vmcnt(0)" ::: "memory");
;     __syncthreads();
;     if (threadIdx.x == 0) {
;         unsigned* bar = b.bar;
;         __builtin_amdgcn_s_waitcnt(0);
;         unsigned nloc = b.st[0], nx = b.st[1];
;         if (nloc == 0u) { xcd_barrier_complete(bar, b.x, nloc, nx); b.st[0] = nloc; b.st[1] = nx; }
.Ls0_other:
	s_mov_b64 exec, s[4:5]
	v_readfirstlane_b32 s6, v188
	s_nop 3
	s_cmp_lg_u32 s6, 64
	s_cbranch_scc1 .LBB0_115
	v_mov_b32_e32 v3, 0x27e08
	ds_read_b32 v2, v3
	s_waitcnt lgkmcnt(0)
	v_readfirstlane_b32 s6, v2
	s_nop 3
	s_cmp_lg_u32 s6, 0
	s_cbranch_scc1 .LBB0_115
	v_and_b32_e32 v0, 63, v188
	v_lshlrev_b32_e32 v1, 2, v0
	v_add_u32_e32 v1, 0x3a00, v1
	v_readlane_b32 s10, v248, 0
	v_readlane_b32 s11, v248, 1
	v_and_b32_e32 v6, 7, v0
	v_lshlrev_b32_e32 v6, 2, v6
	s_nop 4
	global_load_dword v2, v1, s[10:11] sc1
	global_load_dword v3, v1, s[10:11] offset:256 sc1
	global_load_dword v4, v1, s[10:11] offset:512 sc1
	global_load_dword v5, v1, s[10:11] offset:768 sc1
	s_waitcnt vmcnt(0)
	v_min_u32_e32 v8, v2, v3
	v_min3_u32 v8, v8, v4, v5
	v_cmp_eq_u32_e32 vcc, 0, v8
	s_cbranch_vccnz .LBB0_115
	ds_bpermute_b32 v7, v6, v2
	s_waitcnt lgkmcnt(0)
	v_xor_b32_e32 v2, v2, v7
	v_xor_b32_e32 v3, v3, v7
	v_xor_b32_e32 v4, v4, v7
	v_xor_b32_e32 v5, v5, v7
	v_or3_b32 v2, v2, v3, v4
	v_or_b32_e32 v2, v2, v5
	v_mov_b32_e32 v8, 1
	v_lshlrev_b32_e32 v8, v7, v8
	v_cmp_ne_u32_e32 vcc, 0, v2
	s_mov_b64 s[6:7], vcc
	v_readlane_b32 s8, v8, 0
	v_readlane_b32 s9, v8, 1
	s_nop 1
	s_or_b32 s8, s8, s9
	v_readlane_b32 s9, v8, 2
	s_nop 1
	s_or_b32 s8, s8, s9
	v_readlane_b32 s9, v8, 3
	s_nop 1
	s_or_b32 s8, s8, s9
	v_readlane_b32 s9, v8, 4
	s_nop 1
	s_or_b32 s8, s8, s9
	v_readlane_b32 s9, v8, 5
	s_nop 1
	s_or_b32 s8, s8, s9
	v_readlane_b32 s9, v8, 6
	s_nop 1
	s_or_b32 s8, s8, s9
	v_readlane_b32 s9, v8, 7
	s_nop 1
	s_or_b32 s8, s8, s9
	s_bcnt1_i32_b32 s8, s8
	s_cmp_eq_u64 s[6:7], 0
	s_cselect_b32 s9, 1, 0
	s_cmp_eq_u32 s8, 8
	s_cselect_b32 s9, s9, 0
	s_add_u32 s9, s9, 1
	v_mov_b32_e32 v2, s9
	v_mov_b32_e32 v3, 0x27e08
	ds_write_b32 v3, v2

; #define PG8_STAGE(bufoff, gbase, voff) do { _Pragma("unroll") for (int _i = 0; _i < 2; ++_i) \
;         __builtin_amdgcn_global_load_lds((const unsigned*)((const char*)(gbase) + (voff)[_i]), (PG8_LAS unsigned*)(lds + (bufoff) + ldsw + _i * 8192), 16, 0, 0); } while (0)
; #define PG8_WAIT_V(n) asm volatile("s_waitcnt vmcnt(" #n ")" ::: "memory")
; template <class Epi, class Sched, bool ALIGN_EPI = false, bool SP2 = false>
; __device__ __forceinline__ void gemm_phase(PG8_LAS unsigned char* lds, const Gemm g, const Sched& S, const Epi& E) {
;     ...
;     for (int i = 0; i < 2; ++i) { int R, C; stage_rc(tid * 16 + i * 8192, R, C); const int Rb = Epi::PERM ? ((R & ~31) + perm32(R & 31)) : R;
;         voffA[i] = (unsigned)(R * K + C) * 2u; voffB[i] = (unsigned)(Rb * K + C) * 2u; }
;     const size_t kstep = (size_t)(BK * 2);
;     const size_t hstep = (size_t)HALF * K * 2;
;     const size_t tstep = 2 * hstep;
;     const unsigned ldsw = (unsigned)wid * 1024u;
;     const int aoff = lds_byte(wr * 64 + fr, fq * 8), boff = lds_byte(wc * 32 + fr, fq * 8);
;     ...
;     Unit cur, nxt; int ui = 0;
;     if (!S.next(0, cur)) return;
;     f32x4 acc[2][2][4][2];
; #pragma unroll
;     for (int a = 0; a < 2; ++a)
; #pragma unroll
;         for (int b = 0; b < 2; ++b)
; #pragma unroll
;             for (int m = 0; m < 4; ++m)
; #pragma unroll
;                 for (int n = 0; n < 2; ++n) acc[a][b][m][n] = (f32x4){0.f, 0.f, 0.f, 0.f};
;     bf16x8 At[4][2], B0[2][2], B1[2][2];
;     const char* cA = (const char*)g.A + (size_t)cur.pm * tstep; const char* cB = (const char*)g.Bt + (size_t)cur.pn * tstep;
;     S.a_ready(cur);
;     if constexpr (SP2) {
;         PG8_STAGE(PG8_SB(0, 0), cB, voffB); PG8_STAGE(PG8_SB(0, 1), cB + hstep, voffB); PG8_STAGE(PG8_SA(0, 0), cA, voffA); PG8_STAGE(PG8_SA(0, 1), cA + hstep, voffA);
;         if (wr == 1) PG8_BAR;
;         PG8_WAIT_V(2); PG8_BAR;
;         PG8_STAGE(PG8_SB(1, 0), cB + kstep, voffB); PG8_STAGE(PG8_SA(1, 0), cA + kstep, voffA); PG8_STAGE(PG8_SB(1, 1), cB + hstep + kstep, voffB);
;         PG8_WAIT_V(6); PG8_BAR;
;     __device__ __forceinline__ void operator()(const f32x4 (&acc)[2][2][4][2], const Unit& u, int wr, int wc, int fr, int fq) const {
;     ...
;                 const float* cosT = (const float*)(ws + WS_COS); const float* sinT = (const float*)(ws + WS_SIN);
;                 const int jb = 16 * (wc & 1) + 4 * fq;
.LBB0_120:
	s_ashr_i32 s61, s80, 31
	s_add_u32 s10, s76, 0x3000000
	s_mov_b64 s[12:13], 0x80
	s_sext_i32_i16 s94, s0
	s_addc_u32 s11, s77, 0
	s_and_b32 s0, s16, 3
	s_add_i32 m0, s53, 0x18000
	v_lshl_add_u64 v[6:7], v[6:7], 0, s[12:13]
	s_lshl_b32 s15, s14, 13
	s_lshl_b32 s17, s0, 5
	s_lshl_b32 s0, s0, 12
	s_waitcnt vmcnt(2)
	s_barrier
	global_load_lds_dwordx4 v[6:7], off
	v_lshl_add_u64 v[4:5], v[4:5], 0, s[12:13]
	s_add_i32 m0, s53, 0x1a000
	s_add_i32 s62, s53, 0x8000
	s_add_i32 s63, s53, 0xa000
	global_load_lds_dwordx4 v[4:5], off
	v_lshl_add_u64 v[0:1], v[0:1], 0, s[12:13]
	s_mov_b32 m0, s62
	s_add_u32 s18, s42, 0x40080
	global_load_lds_dwordx4 v[0:1], off
	v_lshl_add_u64 v[0:1], v[2:3], 0, s[12:13]
	s_mov_b32 m0, s63
	s_addc_u32 s19, s43, 0
	global_load_lds_dwordx4 v[0:1], off
	s_add_i32 m0, s53, 0x1c000
	v_lshl_add_u64 v[0:1], s[18:19], 0, v[146:147]
	global_load_lds_dwordx4 v[0:1], off
	v_lshl_add_u64 v[0:1], s[18:19], 0, v[150:151]
	s_add_i32 m0, s53, 0x1e000
	s_movk_i32 s18, 0x3c0
	global_load_lds_dwordx4 v[0:1], off
	v_bfe_u32 v0, v188, 4, 2
	v_lshlrev_b32_e32 v1, 3, v0
	v_lshlrev_b32_e32 v2, 4, v0
	v_lshlrev_b32_e32 v0, 6, v188
	v_lshlrev_b32_e32 v3, 2, v188
	v_and_or_b32 v0, v0, s18, v2
	v_and_b32_e32 v3, 32, v3
	v_and_b32_e32 v12, 15, v188
	v_bitop3_b32 v175, s0, v0, v3 bitop3:0xf6
	v_or_b32_e32 v0, s17, v1
	v_lshl_or_b32 v4, v12, 6, v2
	s_cmpk_lt_u32 s1, 0x100
	v_or_b32_e32 v176, 0xffffee00, v0
	v_bitop3_b32 v0, s17, 56, v1 bitop3:0xc8
	v_lshl_or_b32 v174, s14, 6, v12
	v_bitop3_b32 v4, v4, s15, v3 bitop3:0xde
	s_cselect_b64 s[14:15], -1, 0
	s_lshl_b32 s0, s16, 20
	v_lshlrev_b32_e32 v152, 1, v0
	s_and_b32 s69, s0, 0x200000
	v_lshl_add_u64 v[0:1], s[78:79], 0, v[152:153]
	s_mov_b64 s[0:1], 0x4000000
	v_lshl_add_u64 v[154:155], v[0:1], 0, s[0:1]
	s_lshl_b32 s0, s16, 6
	v_and_or_b32 v152, s0, 64, v2
	v_lshl_add_u64 v[0:1], s[76:77], 0, v[152:153]
	s_mov_b64 s[0:1], 0x1000000
	v_lshl_add_u64 v[156:157], v[0:1], 0, s[0:1]
	s_mov_b64 s[0:1], 0x1200000
	v_lshl_add_u64 v[158:159], v[0:1], 0, s[0:1]
	v_lshlrev_b32_e32 v0, 8, v188
	v_and_b32_e32 v0, 0x38000, v0
	v_lshlrev_b32_e32 v1, 11, v10
	v_or3_b32 v0, v8, v0, v1
	v_add_u32_e32 v160, v0, v9
	v_lshlrev_b32_e32 v0, 4, v11
	s_waitcnt vmcnt(6)
	v_and_b32_e32 v0, 0x78000, v0
	v_or3_b32 v0, v8, v0, v1
	s_add_i32 s71, 0, 0x10000
	s_add_i32 s72, 0, 0x14000
	s_mov_b32 s68, s80
	s_bfe_u32 s70, s16, 0x10001
	v_mov_b32_e32 v161, v153
	v_add_u32_e32 v162, v0, v9
	v_mov_b32_e32 v163, v153
	v_mov_b64_e32 v[164:165], 0x500
	v_mov_b64_e32 v[166:167], 0x4ff
	v_add_u32_e32 v177, s71, v175
	v_add_u32_e32 v178, s72, v175
	v_add_u32_e32 v179, 0, v4
	s_mov_b32 s73, 0x20000
	s_mov_b64 s[16:17], 0x24000
	s_mov_b32 s86, 0x24000
	s_mov_b64 s[18:19], 0x28000
	s_mov_b32 s87, 0x28000
	s_mov_b64 s[20:21], 0x2c000
	s_mov_b32 s88, 0x2c000
	s_mov_b32 s89, 0x400000
	s_mov_b32 s90, 0x404000
	s_movk_i32 s91, 0x5000
	s_mov_b32 s92, 0x405000
	s_mov_b64 s[22:23], 0x4000
	s_mov_b64 s[24:25], 0x4800
	s_mov_b64 s[26:27], 0x5000
	s_mov_b64 s[28:29], 0x5800
	v_mov_b32_e32 v180, 0x3e38aa3b
	s_mov_b32 s93, 0
	s_barrier
	s_branch .LBB0_123

; __device__ __forceinline__ void xcd_barrier(const XcdBarrier& b) {
;     asm volatile("s_waitcnt vmcnt(0)" ::: "memory");
;     __syncthreads();
;     if (threadIdx.x == 0) {
;         unsigned* bar = b.bar;
;         __builtin_amdgcn_s_waitcnt(0);
;         unsigned nloc = b.st[0], nx = b.st[1];
.LBB0_141:
	s_cmp_gt_i32 s83, 2
	s_cselect_b64 s[0:1], -1, 0
	s_and_b64 s[4:5], s[4:5], s[0:1]
	s_andn2_b64 vcc, exec, s[4:5]
	s_cbranch_vccnz .LBB0_195
	s_waitcnt vmcnt(0)
	s_waitcnt vmcnt(0) lgkmcnt(0)
	s_barrier
	s_mov_b64 s[4:5], exec
	v_readlane_b32 s6, v248, 2
	v_readlane_b32 s7, v248, 3
	s_and_b64 s[6:7], s[4:5], s[6:7]
	s_mov_b64 exec, s[6:7]
	s_cbranch_execz .Ls1_other
	v_mov_b32_e32 v14, 0x27e08
	s_mov_b32 s99, 0

; __device__ __forceinline__ unsigned xb_ld(unsigned* p)              { return __hip_atomic_load(p, __ATOMIC_RELAXED, __HIP_MEMORY_SCOPE_AGENT); }
; __device__ __forceinline__ unsigned xb_add(unsigned* p, unsigned v) { return __hip_atomic_fetch_add(p, v, __ATOMIC_RELAXED, __HIP_MEMORY_SCOPE_AGENT); }
; #define XB_SPIN(cond, bar) do { unsigned _sp = 0; while (cond) { __builtin_amdgcn_s_sleep(1); \
;     if ((++_sp & 255u) == 0u) { if (xb_ld(&(bar)[XB_TMO])) break; if (_sp > XB_SPIN_CAP) { atomicAdd(&(bar)[XB_TMO], 1u); break; } } } } while (0)
; __device__ __forceinline__ void xcd_barrier(const XcdBarrier& b) {
;     ...
;         const unsigned old = xb_add(&bar[XB_XSUB(b.x)], 1u);
;         const unsigned gen = old / nloc;
;         if (old + 1u == (gen + 1u) * nloc) {
;             __builtin_amdgcn_fence(__ATOMIC_RELEASE, "agent");
;             asm volatile("s_waitcnt vmcnt(0)" ::: "memory");
;             const unsigned og = xb_add(&bar[XB_TOP], 1u);
;             const unsigned tg = og / nx;
;             if (og + 1u == (tg + 1u) * nx) xb_add(&bar[XB_TOPGEN], 1u);
;             else XB_SPIN(xb_ld(&bar[XB_TOPGEN]) == tg, bar);
;             __builtin_amdgcn_fence(__ATOMIC_ACQUIRE, "agent");
;             xb_add(&bar[XB_XGEN(b.x)], 1u);
;             asm volatile("s_waitcnt vmcnt(0)" ::: "memory");
.Ls1_flok:
	s_cmp_lg_u32 s8, 2
	s_cbranch_scc1 .Ls1_slow
	v_readlane_b32 s10, v248, 0
	v_readlane_b32 s11, v248, 1
	s_lshl_b32 s6, s3, 8
	v_mov_b32_e32 v4, 1
	s_add_u32 s6, s10, s6
	s_addc_u32 s7, s11, 0
	v_mov_b32_e32 v5, 0x1000
	s_nop 1
	global_atomic_add v6, v5, v4, s[6:7] offset:1024 sc0
	v_mov_b32_e32 v5, 0x2000
	s_mov_b32 s99, 0
	s_waitcnt vmcnt(0)
	v_lshrrev_b32_e32 v7, 5, v6
	v_and_b32_e32 v8, 31, v6
	v_cmp_eq_u32_e32 vcc, 31, v8
	s_cbranch_vccz .Ls1_spin
	buffer_wbl2 sc1
	s_waitcnt vmcnt(0)
	global_atomic_add v5, v4, s[6:7] offset:1024
	s_branch .Ls1_rel

; __device__ __forceinline__ unsigned xb_ld(unsigned* p)              { return __hip_atomic_load(p, __ATOMIC_RELAXED, __HIP_MEMORY_SCOPE_AGENT); }
; __device__ __forceinline__ unsigned xb_add(unsigned* p, unsigned v) { return __hip_atomic_fetch_add(p, v, __ATOMIC_RELAXED, __HIP_MEMORY_SCOPE_AGENT); }
; #define XB_SPIN(cond, bar) do { unsigned _sp = 0; while (cond) { __builtin_amdgcn_s_sleep(1); \
;     if ((++_sp & 255u) == 0u) { if (xb_ld(&(bar)[XB_TMO])) break; if (_sp > XB_SPIN_CAP) { atomicAdd(&(bar)[XB_TMO], 1u); break; } } } } while (0)
; __device__ __forceinline__ void xcd_barrier(const XcdBarrier& b) {
;     ...
;     if (threadIdx.x == 0) {
;         unsigned* bar = b.bar;
;         __builtin_amdgcn_s_waitcnt(0);
;         unsigned nloc = b.st[0], nx = b.st[1];
;         if (nloc == 0u) { xcd_barrier_complete(bar, b.x, nloc, nx); b.st[0] = nloc; b.st[1] = nx; }
;         const unsigned old = xb_add(&bar[XB_XSUB(b.x)], 1u);
;         const unsigned gen = old / nloc;
;         if (old + 1u == (gen + 1u) * nloc) {
;             __builtin_amdgcn_fence(__ATOMIC_RELEASE, "agent");
;             asm volatile("s_waitcnt vmcnt(0)" ::: "memory");
;             const unsigned og = xb_add(&bar[XB_TOP], 1u);
;             const unsigned tg = og / nx;
;             if (og + 1u == (tg + 1u) * nx) xb_add(&bar[XB_TOPGEN], 1u);
;             else XB_SPIN(xb_ld(&bar[XB_TOPGEN]) == tg, bar);
;             __builtin_amdgcn_fence(__ATOMIC_ACQUIRE, "agent");
;             xb_add(&bar[XB_XGEN(b.x)], 1u);
;             asm volatile("s_waitcnt vmcnt(0)" ::: "memory");
.LBB0_350:
	s_cmp_gt_i32 s83, 4
	s_cselect_b64 s[0:1], -1, 0
	s_and_b64 s[4:5], s[4:5], s[0:1]
	s_andn2_b64 vcc, exec, s[4:5]
	s_cbranch_vccnz .LBB0_404
	s_waitcnt vmcnt(0) lgkmcnt(0)
	s_barrier
	s_mov_b64 s[4:5], exec
	v_readlane_b32 s6, v248, 2
	v_readlane_b32 s7, v248, 3
	s_and_b64 s[6:7], s[4:5], s[6:7]
	s_mov_b64 exec, s[6:7]
	s_cbranch_execz .Ls3_close
	s_add_i32 s6, 0, 0x27e00
	v_mov_b32_e32 v0, s6
	ds_read2_b32 v[2:3], v0 offset1:1
	ds_read_b32 v13, v0 offset:8
	v_readlane_b32 s10, v248, 0
	v_readlane_b32 s11, v248, 1
	s_lshl_b32 s6, s3, 8
	s_nop 1
	s_add_u32 s6, s10, s6
	s_addc_u32 s7, s11, 0
	v_mov_b32_e32 v4, 1
	v_mov_b32_e32 v5, 0x1000
	global_atomic_add v6, v5, v4, s[6:7] offset:1024 sc0
	s_waitcnt vmcnt(0) lgkmcnt(0)
	v_cvt_f32_u32_e32 v7, v2
	v_sub_u32_e32 v8, 0, v2
	v_rcp_iflag_f32_e32 v7, v7
	s_nop 0
	v_mul_f32_e32 v7, 0x4f7ffffe, v7
	v_cvt_u32_f32_e32 v7, v7
	v_mul_lo_u32 v8, v8, v7
	v_mul_hi_u32 v8, v7, v8
	v_add_u32_e32 v7, v7, v8
	v_mul_hi_u32 v7, v6, v7
	v_mul_lo_u32 v8, v7, v2
	v_sub_u32_e32 v8, v6, v8
	v_add_u32_e32 v9, 1, v7
	v_cmp_ge_u32_e32 vcc, v8, v2
	s_nop 1
	v_cndmask_b32_e32 v7, v7, v9, vcc
	v_sub_u32_e32 v9, v8, v2
	v_cndmask_b32_e32 v8, v8, v9, vcc
	v_add_u32_e32 v9, 1, v7
	v_cmp_ge_u32_e32 vcc, v8, v2
	s_nop 1
	v_cndmask_b32_e32 v7, v7, v9, vcc
	v_add_u32_e32 v9, 1, v7
	v_readfirstlane_b32 s98, v7
	v_readfirstlane_b32 s101, v13
	s_nop 3
	s_cmp_eq_u32 s101, 2
	s_cselect_b32 s100, 1, 0
	v_subrev_u32_e32 v16, s100, v7
	s_sub_u32 s98, s98, s100
	v_mul_lo_u32 v9, v9, v2
	v_add_u32_e32 v10, 1, v6
	v_cmp_eq_u32_e32 vcc, v10, v9
	s_cbranch_vccz .Ls3_notleader
	buffer_wbl2 sc1
	s_waitcnt vmcnt(0)
	v_mov_b32_e32 v5, 0x2000
	global_atomic_add v5, v4, s[6:7] offset:1024
	v_mov_b32_e32 v5, 0x3000
	global_atomic_add v11, v5, v4, s[10:11] offset:1024 sc0
	v_add_u32_e32 v9, 1, v16
	v_mul_lo_u32 v9, v9, v3
	s_waitcnt vmcnt(0)
	v_add_u32_e32 v10, 1, v11
	v_cmp_eq_u32_e32 vcc, v10, v9
	s_cbranch_vccz .Ls3_notleader
	global_atomic_add v5, v4, s[10:11] offset:1280

; __device__ __forceinline__ unsigned xb_ld(unsigned* p)              { return __hip_atomic_load(p, __ATOMIC_RELAXED, __HIP_MEMORY_SCOPE_AGENT); }
; #define XB_SPIN(cond, bar) do { unsigned _sp = 0; while (cond) { __builtin_amdgcn_s_sleep(1); \
;     if ((++_sp & 255u) == 0u) { if (xb_ld(&(bar)[XB_TMO])) break; if (_sp > XB_SPIN_CAP) { atomicAdd(&(bar)[XB_TMO], 1u); break; } } } } while (0)
; __device__ __forceinline__ void xcd_barrier(const XcdBarrier& b) {
;     ...
;         } else {
;             XB_SPIN(xb_ld(&bar[XB_XGEN(b.x)]) == gen, bar);
;             __builtin_amdgcn_fence(__ATOMIC_ACQUIRE, "agent");
;             asm volatile("s_waitcnt vmcnt(0)" ::: "memory");
;         }
;     }
;     __syncthreads();
.Ls3_spin:
	global_load_dword v12, v5, s[10:11] offset:1280 sc1
	s_waitcnt vmcnt(0)
	v_cmp_ne_u32_e32 vcc, v12, v16
	s_cbranch_vccnz .Ls3_released
	s_add_u32 s99, s99, 1
	s_cmp_gt_u32 s99, 0x40000
	s_cbranch_scc1 .Ls3_released
	s_sleep 1
	s_branch .Ls3_spin
.Ls3_released:
	s_waitcnt vmcnt(0)
	buffer_inv sc1
	s_waitcnt vmcnt(0)
	s_branch .Ls3_close
.Ls3_close:
	s_mov_b64 exec, s[4:5]
	s_waitcnt lgkmcnt(0)
	s_barrier
